# gemm_in gate column tiles (24 of 53): own sigmoid epilogue for both tiles with paired 16-byte stores
# speedup vs baseline: 1.0293x; 1.0093x over previous
.Lg2_nopf:
	s_cmp_lt_u32 s37, 29
	s_cbranch_scc1 .Lg2_2p
	s_load_dwordx2 s[92:93], s[84:85], 0x198
	s_load_dwordx2 s[98:99], s[84:85], 0x58
	v_lshrrev_b32_e32 v148, 7, v196
	v_and_b32_e32 v149, 15, v196
	v_lshl_or_b32 v148, v148, 6, v149
	v_mul_u32_u24_e32 v148, 0x1800, v148
	v_bfe_u32 v149, v196, 6, 1
	v_bfe_u32 v150, v196, 4, 2
	v_lshlrev_b32_e32 v160, 8, v149
	v_lshl_or_b32 v160, v150, 4, v160
	v_lshlrev_b32_e32 v149, 7, v149
	v_lshl_or_b32 v149, v150, 3, v149
	v_and_b32_e32 v150, 1, v150
	v_mul_u32_u24_e32 v150, 24, v150
	v_add3_u32 v156, v148, v149, v150
	v_add_u32_e32 v157, 0x18000, v156
	v_add_u32_e32 v158, 0x30000, v156
	v_add_u32_e32 v159, 0x48000, v156
	v_readlane_b32 s2, v249, 52
	s_sub_i32 s3, s37, 29
	s_mul_i32 s2, s2, 0x3000
	s_lshl_b32 s20, s3, 9
	s_add_i32 s2, s2, s20
	s_waitcnt lgkmcnt(0)
	s_add_u32 s98, s98, s2
	s_addc_u32 s99, s99, 0
	global_load_dwordx4 v[188:191], v160, s[98:99]
	global_load_dwordx4 v[192:195], v160, s[98:99] offset:64
	global_load_dwordx4 v[208:211], v160, s[98:99] offset:128
	global_load_dwordx4 v[212:215], v160, s[98:99] offset:192
	s_lshl_b32 s20, s3, 8
	s_mul_i32 s2, s0, 0xc0000
	s_add_i32 s2, s2, s20
	s_add_u32 s96, s92, s2
	s_addc_u32 s97, s93, 0
	s_waitcnt vmcnt(0)
	v_pk_add_f32 v[148:149], v[62:63], v[188:189]
	v_pk_add_f32 v[150:151], v[64:65], v[190:191]
	v_mul_f32_e32 v148, 0xbfb8aa3b, v148
	v_mul_f32_e32 v149, 0xbfb8aa3b, v149
	v_mul_f32_e32 v150, 0xbfb8aa3b, v150
	v_mul_f32_e32 v151, 0xbfb8aa3b, v151
	v_exp_f32_e32 v148, v148
	v_exp_f32_e32 v149, v149
	v_exp_f32_e32 v150, v150
	v_exp_f32_e32 v151, v151
	v_add_f32_e32 v148, 1.0, v148
	v_add_f32_e32 v149, 1.0, v149
	v_add_f32_e32 v150, 1.0, v150
	v_add_f32_e32 v151, 1.0, v151
	v_rcp_f32_e32 v148, v148
	v_rcp_f32_e32 v149, v149
	v_rcp_f32_e32 v150, v150
	v_rcp_f32_e32 v151, v151
	s_nop 0
	v_cvt_pk_bf16_f32 v164, v148, v149
	v_cvt_pk_bf16_f32 v165, v150, v151
	v_pk_add_f32 v[148:149], v[58:59], v[192:193]
	v_pk_add_f32 v[150:151], v[60:61], v[194:195]
	v_mul_f32_e32 v148, 0xbfb8aa3b, v148
	v_mul_f32_e32 v149, 0xbfb8aa3b, v149
	v_mul_f32_e32 v150, 0xbfb8aa3b, v150
	v_mul_f32_e32 v151, 0xbfb8aa3b, v151
	v_exp_f32_e32 v148, v148
	v_exp_f32_e32 v149, v149
	v_exp_f32_e32 v150, v150
	v_exp_f32_e32 v151, v151
	v_add_f32_e32 v148, 1.0, v148
	v_add_f32_e32 v149, 1.0, v149
	v_add_f32_e32 v150, 1.0, v150
	v_add_f32_e32 v151, 1.0, v151
	v_rcp_f32_e32 v148, v148
	v_rcp_f32_e32 v149, v149
	v_rcp_f32_e32 v150, v150
	v_rcp_f32_e32 v151, v151
	s_nop 0
	v_cvt_pk_bf16_f32 v166, v148, v149
	v_cvt_pk_bf16_f32 v167, v150, v151
	s_nop 1
	v_permlane16_swap_b32 v164, v166
	v_permlane16_swap_b32 v165, v167
	s_nop 1
	global_store_dwordx4 v156, v[164:167], s[96:97]
	v_pk_add_f32 v[148:149], v[54:55], v[208:209]
	v_pk_add_f32 v[150:151], v[56:57], v[210:211]
	v_mul_f32_e32 v148, 0xbfb8aa3b, v148
	v_mul_f32_e32 v149, 0xbfb8aa3b, v149
	v_mul_f32_e32 v150, 0xbfb8aa3b, v150
	v_mul_f32_e32 v151, 0xbfb8aa3b, v151
	v_exp_f32_e32 v148, v148
	v_exp_f32_e32 v149, v149
	v_exp_f32_e32 v150, v150
	v_exp_f32_e32 v151, v151
	v_add_f32_e32 v148, 1.0, v148
	v_add_f32_e32 v149, 1.0, v149
	v_add_f32_e32 v150, 1.0, v150
	v_add_f32_e32 v151, 1.0, v151
	v_rcp_f32_e32 v148, v148
	v_rcp_f32_e32 v149, v149
	v_rcp_f32_e32 v150, v150
	v_rcp_f32_e32 v151, v151
	s_nop 0
	v_cvt_pk_bf16_f32 v168, v148, v149
	v_cvt_pk_bf16_f32 v169, v150, v151
	v_pk_add_f32 v[148:149], v[50:51], v[212:213]
	v_pk_add_f32 v[150:151], v[52:53], v[214:215]
	v_mul_f32_e32 v148, 0xbfb8aa3b, v148
	v_mul_f32_e32 v149, 0xbfb8aa3b, v149
	v_mul_f32_e32 v150, 0xbfb8aa3b, v150
	v_mul_f32_e32 v151, 0xbfb8aa3b, v151
	v_exp_f32_e32 v148, v148
	v_exp_f32_e32 v149, v149
	v_exp_f32_e32 v150, v150
	v_exp_f32_e32 v151, v151
	v_add_f32_e32 v148, 1.0, v148
	v_add_f32_e32 v149, 1.0, v149
	v_add_f32_e32 v150, 1.0, v150
	v_add_f32_e32 v151, 1.0, v151
	v_rcp_f32_e32 v148, v148
	v_rcp_f32_e32 v149, v149
	v_rcp_f32_e32 v150, v150
	v_rcp_f32_e32 v151, v151
	s_nop 0
	v_cvt_pk_bf16_f32 v170, v148, v149
	v_cvt_pk_bf16_f32 v171, v150, v151
	s_nop 1
	v_permlane16_swap_b32 v168, v170
	v_permlane16_swap_b32 v169, v171
	s_nop 1
	global_store_dwordx4 v156, v[168:171], s[96:97] offset:64
	v_pk_add_f32 v[148:149], v[46:47], v[188:189]
	v_pk_add_f32 v[150:151], v[48:49], v[190:191]
	v_mul_f32_e32 v148, 0xbfb8aa3b, v148
	v_mul_f32_e32 v149, 0xbfb8aa3b, v149
	v_mul_f32_e32 v150, 0xbfb8aa3b, v150
	v_mul_f32_e32 v151, 0xbfb8aa3b, v151
	v_exp_f32_e32 v148, v148
	v_exp_f32_e32 v149, v149
	v_exp_f32_e32 v150, v150
	v_exp_f32_e32 v151, v151
	v_add_f32_e32 v148, 1.0, v148
	v_add_f32_e32 v149, 1.0, v149
	v_add_f32_e32 v150, 1.0, v150
	v_add_f32_e32 v151, 1.0, v151
	v_rcp_f32_e32 v148, v148
	v_rcp_f32_e32 v149, v149
	v_rcp_f32_e32 v150, v150
	v_rcp_f32_e32 v151, v151
	s_nop 0
	v_cvt_pk_bf16_f32 v164, v148, v149
	v_cvt_pk_bf16_f32 v165, v150, v151
	v_pk_add_f32 v[148:149], v[42:43], v[192:193]
	v_pk_add_f32 v[150:151], v[44:45], v[194:195]
	v_mul_f32_e32 v148, 0xbfb8aa3b, v148
	v_mul_f32_e32 v149, 0xbfb8aa3b, v149
	v_mul_f32_e32 v150, 0xbfb8aa3b, v150
	v_mul_f32_e32 v151, 0xbfb8aa3b, v151
	v_exp_f32_e32 v148, v148
	v_exp_f32_e32 v149, v149
	v_exp_f32_e32 v150, v150
	v_exp_f32_e32 v151, v151
	v_add_f32_e32 v148, 1.0, v148
	v_add_f32_e32 v149, 1.0, v149
	v_add_f32_e32 v150, 1.0, v150
	v_add_f32_e32 v151, 1.0, v151
	v_rcp_f32_e32 v148, v148
	v_rcp_f32_e32 v149, v149
	v_rcp_f32_e32 v150, v150
	v_rcp_f32_e32 v151, v151
	s_nop 0
	v_cvt_pk_bf16_f32 v166, v148, v149
	v_cvt_pk_bf16_f32 v167, v150, v151
	s_nop 1
	v_permlane16_swap_b32 v164, v166
	v_permlane16_swap_b32 v165, v167
	s_nop 1
	global_store_dwordx4 v157, v[164:167], s[96:97]
	v_pk_add_f32 v[148:149], v[38:39], v[208:209]
	v_pk_add_f32 v[150:151], v[40:41], v[210:211]
	v_mul_f32_e32 v148, 0xbfb8aa3b, v148
	v_mul_f32_e32 v149, 0xbfb8aa3b, v149
	v_mul_f32_e32 v150, 0xbfb8aa3b, v150
	v_mul_f32_e32 v151, 0xbfb8aa3b, v151
	v_exp_f32_e32 v148, v148
	v_exp_f32_e32 v149, v149
	v_exp_f32_e32 v150, v150
	v_exp_f32_e32 v151, v151
	v_add_f32_e32 v148, 1.0, v148
	v_add_f32_e32 v149, 1.0, v149
	v_add_f32_e32 v150, 1.0, v150
	v_add_f32_e32 v151, 1.0, v151
	v_rcp_f32_e32 v148, v148
	v_rcp_f32_e32 v149, v149
	v_rcp_f32_e32 v150, v150
	v_rcp_f32_e32 v151, v151
	s_nop 0
	v_cvt_pk_bf16_f32 v168, v148, v149
	v_cvt_pk_bf16_f32 v169, v150, v151
	v_pk_add_f32 v[148:149], v[34:35], v[212:213]
	v_pk_add_f32 v[150:151], v[36:37], v[214:215]
	v_mul_f32_e32 v148, 0xbfb8aa3b, v148
	v_mul_f32_e32 v149, 0xbfb8aa3b, v149
	v_mul_f32_e32 v150, 0xbfb8aa3b, v150
	v_mul_f32_e32 v151, 0xbfb8aa3b, v151
	v_exp_f32_e32 v148, v148
	v_exp_f32_e32 v149, v149
	v_exp_f32_e32 v150, v150
	v_exp_f32_e32 v151, v151
	v_add_f32_e32 v148, 1.0, v148
	v_add_f32_e32 v149, 1.0, v149
	v_add_f32_e32 v150, 1.0, v150
	v_add_f32_e32 v151, 1.0, v151
	v_rcp_f32_e32 v148, v148
	v_rcp_f32_e32 v149, v149
	v_rcp_f32_e32 v150, v150
	v_rcp_f32_e32 v151, v151
	s_nop 0
	v_cvt_pk_bf16_f32 v170, v148, v149
	v_cvt_pk_bf16_f32 v171, v150, v151
	s_nop 1
	v_permlane16_swap_b32 v168, v170
	v_permlane16_swap_b32 v169, v171
	s_nop 1
	global_store_dwordx4 v157, v[168:171], s[96:97] offset:64
	v_pk_add_f32 v[148:149], v[30:31], v[188:189]
	v_pk_add_f32 v[150:151], v[32:33], v[190:191]
	v_mul_f32_e32 v148, 0xbfb8aa3b, v148
	v_mul_f32_e32 v149, 0xbfb8aa3b, v149
	v_mul_f32_e32 v150, 0xbfb8aa3b, v150
	v_mul_f32_e32 v151, 0xbfb8aa3b, v151
	v_exp_f32_e32 v148, v148
	v_exp_f32_e32 v149, v149
	v_exp_f32_e32 v150, v150
	v_exp_f32_e32 v151, v151
	v_add_f32_e32 v148, 1.0, v148
	v_add_f32_e32 v149, 1.0, v149
	v_add_f32_e32 v150, 1.0, v150
	v_add_f32_e32 v151, 1.0, v151
	v_rcp_f32_e32 v148, v148
	v_rcp_f32_e32 v149, v149
	v_rcp_f32_e32 v150, v150
	v_rcp_f32_e32 v151, v151
	s_nop 0
	v_cvt_pk_bf16_f32 v164, v148, v149
	v_cvt_pk_bf16_f32 v165, v150, v151
	v_pk_add_f32 v[148:149], v[26:27], v[192:193]
	v_pk_add_f32 v[150:151], v[28:29], v[194:195]
	v_mul_f32_e32 v148, 0xbfb8aa3b, v148
	v_mul_f32_e32 v149, 0xbfb8aa3b, v149
	v_mul_f32_e32 v150, 0xbfb8aa3b, v150
	v_mul_f32_e32 v151, 0xbfb8aa3b, v151
	v_exp_f32_e32 v148, v148
	v_exp_f32_e32 v149, v149
	v_exp_f32_e32 v150, v150
	v_exp_f32_e32 v151, v151
	v_add_f32_e32 v148, 1.0, v148
	v_add_f32_e32 v149, 1.0, v149
	v_add_f32_e32 v150, 1.0, v150
	v_add_f32_e32 v151, 1.0, v151
	v_rcp_f32_e32 v148, v148
	v_rcp_f32_e32 v149, v149
	v_rcp_f32_e32 v150, v150
	v_rcp_f32_e32 v151, v151
	s_nop 0
	v_cvt_pk_bf16_f32 v166, v148, v149
	v_cvt_pk_bf16_f32 v167, v150, v151
	s_nop 1
	v_permlane16_swap_b32 v164, v166
	v_permlane16_swap_b32 v165, v167
	s_nop 1
	global_store_dwordx4 v158, v[164:167], s[96:97]
	v_pk_add_f32 v[148:149], v[22:23], v[208:209]
	v_pk_add_f32 v[150:151], v[24:25], v[210:211]
	v_mul_f32_e32 v148, 0xbfb8aa3b, v148
	v_mul_f32_e32 v149, 0xbfb8aa3b, v149
	v_mul_f32_e32 v150, 0xbfb8aa3b, v150
	v_mul_f32_e32 v151, 0xbfb8aa3b, v151
	v_exp_f32_e32 v148, v148
	v_exp_f32_e32 v149, v149
	v_exp_f32_e32 v150, v150
	v_exp_f32_e32 v151, v151
	v_add_f32_e32 v148, 1.0, v148
	v_add_f32_e32 v149, 1.0, v149
	v_add_f32_e32 v150, 1.0, v150
	v_add_f32_e32 v151, 1.0, v151
	v_rcp_f32_e32 v148, v148
	v_rcp_f32_e32 v149, v149
	v_rcp_f32_e32 v150, v150
	v_rcp_f32_e32 v151, v151
	s_nop 0
	v_cvt_pk_bf16_f32 v168, v148, v149
	v_cvt_pk_bf16_f32 v169, v150, v151
	v_pk_add_f32 v[148:149], v[18:19], v[212:213]
	v_pk_add_f32 v[150:151], v[20:21], v[214:215]
	v_mul_f32_e32 v148, 0xbfb8aa3b, v148
	v_mul_f32_e32 v149, 0xbfb8aa3b, v149
	v_mul_f32_e32 v150, 0xbfb8aa3b, v150
	v_mul_f32_e32 v151, 0xbfb8aa3b, v151
	v_exp_f32_e32 v148, v148
	v_exp_f32_e32 v149, v149
	v_exp_f32_e32 v150, v150
	v_exp_f32_e32 v151, v151
	v_add_f32_e32 v148, 1.0, v148
	v_add_f32_e32 v149, 1.0, v149
	v_add_f32_e32 v150, 1.0, v150
	v_add_f32_e32 v151, 1.0, v151
	v_rcp_f32_e32 v148, v148
	v_rcp_f32_e32 v149, v149
	v_rcp_f32_e32 v150, v150
	v_rcp_f32_e32 v151, v151
	s_nop 0
	v_cvt_pk_bf16_f32 v170, v148, v149
	v_cvt_pk_bf16_f32 v171, v150, v151
	s_nop 1
	v_permlane16_swap_b32 v168, v170
	v_permlane16_swap_b32 v169, v171
	s_nop 1
	global_store_dwordx4 v158, v[168:171], s[96:97] offset:64
	v_pk_add_f32 v[148:149], v[14:15], v[188:189]
	v_pk_add_f32 v[150:151], v[16:17], v[190:191]
	v_mul_f32_e32 v148, 0xbfb8aa3b, v148
	v_mul_f32_e32 v149, 0xbfb8aa3b, v149
	v_mul_f32_e32 v150, 0xbfb8aa3b, v150
	v_mul_f32_e32 v151, 0xbfb8aa3b, v151
	v_exp_f32_e32 v148, v148
	v_exp_f32_e32 v149, v149
	v_exp_f32_e32 v150, v150
	v_exp_f32_e32 v151, v151
	v_add_f32_e32 v148, 1.0, v148
	v_add_f32_e32 v149, 1.0, v149
	v_add_f32_e32 v150, 1.0, v150
	v_add_f32_e32 v151, 1.0, v151
	v_rcp_f32_e32 v148, v148
	v_rcp_f32_e32 v149, v149
	v_rcp_f32_e32 v150, v150
	v_rcp_f32_e32 v151, v151
	s_nop 0
	v_cvt_pk_bf16_f32 v164, v148, v149
	v_cvt_pk_bf16_f32 v165, v150, v151
	v_pk_add_f32 v[148:149], v[10:11], v[192:193]
	v_pk_add_f32 v[150:151], v[12:13], v[194:195]
	v_mul_f32_e32 v148, 0xbfb8aa3b, v148
	v_mul_f32_e32 v149, 0xbfb8aa3b, v149
	v_mul_f32_e32 v150, 0xbfb8aa3b, v150
	v_mul_f32_e32 v151, 0xbfb8aa3b, v151
	v_exp_f32_e32 v148, v148
	v_exp_f32_e32 v149, v149
	v_exp_f32_e32 v150, v150
	v_exp_f32_e32 v151, v151
	v_add_f32_e32 v148, 1.0, v148
	v_add_f32_e32 v149, 1.0, v149
	v_add_f32_e32 v150, 1.0, v150
	v_add_f32_e32 v151, 1.0, v151
	v_rcp_f32_e32 v148, v148
	v_rcp_f32_e32 v149, v149
	v_rcp_f32_e32 v150, v150
	v_rcp_f32_e32 v151, v151
	s_nop 0
	v_cvt_pk_bf16_f32 v166, v148, v149
	v_cvt_pk_bf16_f32 v167, v150, v151
	s_nop 1
	v_permlane16_swap_b32 v164, v166
	v_permlane16_swap_b32 v165, v167
	s_nop 1
	global_store_dwordx4 v159, v[164:167], s[96:97]
	v_pk_add_f32 v[148:149], v[6:7], v[208:209]
	v_pk_add_f32 v[150:151], v[8:9], v[210:211]
	v_mul_f32_e32 v148, 0xbfb8aa3b, v148
	v_mul_f32_e32 v149, 0xbfb8aa3b, v149
	v_mul_f32_e32 v150, 0xbfb8aa3b, v150
	v_mul_f32_e32 v151, 0xbfb8aa3b, v151
	v_exp_f32_e32 v148, v148
	v_exp_f32_e32 v149, v149
	v_exp_f32_e32 v150, v150
	v_exp_f32_e32 v151, v151
	v_add_f32_e32 v148, 1.0, v148
	v_add_f32_e32 v149, 1.0, v149
	v_add_f32_e32 v150, 1.0, v150
	v_add_f32_e32 v151, 1.0, v151
	v_rcp_f32_e32 v148, v148
	v_rcp_f32_e32 v149, v149
	v_rcp_f32_e32 v150, v150
	v_rcp_f32_e32 v151, v151
	s_nop 0
	v_cvt_pk_bf16_f32 v168, v148, v149
	v_cvt_pk_bf16_f32 v169, v150, v151
	v_pk_add_f32 v[148:149], v[2:3], v[212:213]
	v_pk_add_f32 v[150:151], v[4:5], v[214:215]
	v_mul_f32_e32 v148, 0xbfb8aa3b, v148
	v_mul_f32_e32 v149, 0xbfb8aa3b, v149
	v_mul_f32_e32 v150, 0xbfb8aa3b, v150
	v_mul_f32_e32 v151, 0xbfb8aa3b, v151
	v_exp_f32_e32 v148, v148
	v_exp_f32_e32 v149, v149
	v_exp_f32_e32 v150, v150
	v_exp_f32_e32 v151, v151
	v_add_f32_e32 v148, 1.0, v148
	v_add_f32_e32 v149, 1.0, v149
	v_add_f32_e32 v150, 1.0, v150
	v_add_f32_e32 v151, 1.0, v151
	v_rcp_f32_e32 v148, v148
	v_rcp_f32_e32 v149, v149
	v_rcp_f32_e32 v150, v150
	v_rcp_f32_e32 v151, v151
	s_nop 0
	v_cvt_pk_bf16_f32 v170, v148, v149
	v_cvt_pk_bf16_f32 v171, v150, v151
	s_nop 1
	v_permlane16_swap_b32 v168, v170
	v_permlane16_swap_b32 v169, v171
	s_nop 1
	global_store_dwordx4 v159, v[168:171], s[96:97] offset:64
	s_mul_i32 s2, s49, 0xc0000
	s_add_i32 s2, s2, s20
	s_add_u32 s96, s92, s2
	s_addc_u32 s97, s93, 0
	v_pk_add_f32 v[148:149], v[66:67], v[188:189]
	v_pk_add_f32 v[150:151], v[68:69], v[190:191]
	v_mul_f32_e32 v148, 0xbfb8aa3b, v148
	v_mul_f32_e32 v149, 0xbfb8aa3b, v149
	v_mul_f32_e32 v150, 0xbfb8aa3b, v150
	v_mul_f32_e32 v151, 0xbfb8aa3b, v151
	v_exp_f32_e32 v148, v148
	v_exp_f32_e32 v149, v149
	v_exp_f32_e32 v150, v150
	v_exp_f32_e32 v151, v151
	v_add_f32_e32 v148, 1.0, v148
	v_add_f32_e32 v149, 1.0, v149
	v_add_f32_e32 v150, 1.0, v150
	v_add_f32_e32 v151, 1.0, v151
	v_rcp_f32_e32 v148, v148
	v_rcp_f32_e32 v149, v149
	v_rcp_f32_e32 v150, v150
	v_rcp_f32_e32 v151, v151
	s_nop 0
	v_cvt_pk_bf16_f32 v164, v148, v149
	v_cvt_pk_bf16_f32 v165, v150, v151
	v_pk_add_f32 v[148:149], v[70:71], v[192:193]
	v_pk_add_f32 v[150:151], v[72:73], v[194:195]
	v_mul_f32_e32 v148, 0xbfb8aa3b, v148
	v_mul_f32_e32 v149, 0xbfb8aa3b, v149
	v_mul_f32_e32 v150, 0xbfb8aa3b, v150
	v_mul_f32_e32 v151, 0xbfb8aa3b, v151
	v_exp_f32_e32 v148, v148
	v_exp_f32_e32 v149, v149
	v_exp_f32_e32 v150, v150
	v_exp_f32_e32 v151, v151
	v_add_f32_e32 v148, 1.0, v148
	v_add_f32_e32 v149, 1.0, v149
	v_add_f32_e32 v150, 1.0, v150
	v_add_f32_e32 v151, 1.0, v151
	v_rcp_f32_e32 v148, v148
	v_rcp_f32_e32 v149, v149
	v_rcp_f32_e32 v150, v150
	v_rcp_f32_e32 v151, v151
	s_nop 0
	v_cvt_pk_bf16_f32 v166, v148, v149
	v_cvt_pk_bf16_f32 v167, v150, v151
	s_nop 1
	v_permlane16_swap_b32 v164, v166
	v_permlane16_swap_b32 v165, v167
	s_nop 1
	global_store_dwordx4 v156, v[164:167], s[96:97]
	v_pk_add_f32 v[148:149], v[82:83], v[208:209]
	v_pk_add_f32 v[150:151], v[84:85], v[210:211]
	v_mul_f32_e32 v148, 0xbfb8aa3b, v148
	v_mul_f32_e32 v149, 0xbfb8aa3b, v149
	v_mul_f32_e32 v150, 0xbfb8aa3b, v150
	v_mul_f32_e32 v151, 0xbfb8aa3b, v151
	v_exp_f32_e32 v148, v148
	v_exp_f32_e32 v149, v149
	v_exp_f32_e32 v150, v150
	v_exp_f32_e32 v151, v151
	v_add_f32_e32 v148, 1.0, v148
	v_add_f32_e32 v149, 1.0, v149
	v_add_f32_e32 v150, 1.0, v150
	v_add_f32_e32 v151, 1.0, v151
	v_rcp_f32_e32 v148, v148
	v_rcp_f32_e32 v149, v149
	v_rcp_f32_e32 v150, v150
	v_rcp_f32_e32 v151, v151
	s_nop 0
	v_cvt_pk_bf16_f32 v168, v148, v149
	v_cvt_pk_bf16_f32 v169, v150, v151
	v_pk_add_f32 v[148:149], v[88:89], v[212:213]
	v_pk_add_f32 v[150:151], v[90:91], v[214:215]
	v_mul_f32_e32 v148, 0xbfb8aa3b, v148
	v_mul_f32_e32 v149, 0xbfb8aa3b, v149
	v_mul_f32_e32 v150, 0xbfb8aa3b, v150
	v_mul_f32_e32 v151, 0xbfb8aa3b, v151
	v_exp_f32_e32 v148, v148
	v_exp_f32_e32 v149, v149
	v_exp_f32_e32 v150, v150
	v_exp_f32_e32 v151, v151
	v_add_f32_e32 v148, 1.0, v148
	v_add_f32_e32 v149, 1.0, v149
	v_add_f32_e32 v150, 1.0, v150
	v_add_f32_e32 v151, 1.0, v151
	v_rcp_f32_e32 v148, v148
	v_rcp_f32_e32 v149, v149
	v_rcp_f32_e32 v150, v150
	v_rcp_f32_e32 v151, v151
	s_nop 0
	v_cvt_pk_bf16_f32 v170, v148, v149
	v_cvt_pk_bf16_f32 v171, v150, v151
	s_nop 1
	v_permlane16_swap_b32 v168, v170
	v_permlane16_swap_b32 v169, v171
	s_nop 1
	global_store_dwordx4 v156, v[168:171], s[96:97] offset:64
	v_pk_add_f32 v[148:149], v[92:93], v[188:189]
	v_pk_add_f32 v[150:151], v[94:95], v[190:191]
	v_mul_f32_e32 v148, 0xbfb8aa3b, v148
	v_mul_f32_e32 v149, 0xbfb8aa3b, v149
	v_mul_f32_e32 v150, 0xbfb8aa3b, v150
	v_mul_f32_e32 v151, 0xbfb8aa3b, v151
	v_exp_f32_e32 v148, v148
	v_exp_f32_e32 v149, v149
	v_exp_f32_e32 v150, v150
	v_exp_f32_e32 v151, v151
	v_add_f32_e32 v148, 1.0, v148
	v_add_f32_e32 v149, 1.0, v149
	v_add_f32_e32 v150, 1.0, v150
	v_add_f32_e32 v151, 1.0, v151
	v_rcp_f32_e32 v148, v148
	v_rcp_f32_e32 v149, v149
	v_rcp_f32_e32 v150, v150
	v_rcp_f32_e32 v151, v151
	s_nop 0
	v_cvt_pk_bf16_f32 v164, v148, v149
	v_cvt_pk_bf16_f32 v165, v150, v151
	v_pk_add_f32 v[148:149], v[96:97], v[192:193]
	v_pk_add_f32 v[150:151], v[98:99], v[194:195]
	v_mul_f32_e32 v148, 0xbfb8aa3b, v148
	v_mul_f32_e32 v149, 0xbfb8aa3b, v149
	v_mul_f32_e32 v150, 0xbfb8aa3b, v150
	v_mul_f32_e32 v151, 0xbfb8aa3b, v151
	v_exp_f32_e32 v148, v148
	v_exp_f32_e32 v149, v149
	v_exp_f32_e32 v150, v150
	v_exp_f32_e32 v151, v151
	v_add_f32_e32 v148, 1.0, v148
	v_add_f32_e32 v149, 1.0, v149
	v_add_f32_e32 v150, 1.0, v150
	v_add_f32_e32 v151, 1.0, v151
	v_rcp_f32_e32 v148, v148
	v_rcp_f32_e32 v149, v149
	v_rcp_f32_e32 v150, v150
	v_rcp_f32_e32 v151, v151
	s_nop 0
	v_cvt_pk_bf16_f32 v166, v148, v149
	v_cvt_pk_bf16_f32 v167, v150, v151
	s_nop 1
	v_permlane16_swap_b32 v164, v166
	v_permlane16_swap_b32 v165, v167
	s_nop 1
	global_store_dwordx4 v157, v[164:167], s[96:97]
	v_pk_add_f32 v[148:149], v[100:101], v[208:209]
	v_pk_add_f32 v[150:151], v[102:103], v[210:211]
	v_mul_f32_e32 v148, 0xbfb8aa3b, v148
	v_mul_f32_e32 v149, 0xbfb8aa3b, v149
	v_mul_f32_e32 v150, 0xbfb8aa3b, v150
	v_mul_f32_e32 v151, 0xbfb8aa3b, v151
	v_exp_f32_e32 v148, v148
	v_exp_f32_e32 v149, v149
	v_exp_f32_e32 v150, v150
	v_exp_f32_e32 v151, v151
	v_add_f32_e32 v148, 1.0, v148
	v_add_f32_e32 v149, 1.0, v149
	v_add_f32_e32 v150, 1.0, v150
	v_add_f32_e32 v151, 1.0, v151
	v_rcp_f32_e32 v148, v148
	v_rcp_f32_e32 v149, v149
	v_rcp_f32_e32 v150, v150
	v_rcp_f32_e32 v151, v151
	s_nop 0
	v_cvt_pk_bf16_f32 v168, v148, v149
	v_cvt_pk_bf16_f32 v169, v150, v151
	v_pk_add_f32 v[148:149], v[106:107], v[212:213]
	v_pk_add_f32 v[150:151], v[108:109], v[214:215]
	v_mul_f32_e32 v148, 0xbfb8aa3b, v148
	v_mul_f32_e32 v149, 0xbfb8aa3b, v149
	v_mul_f32_e32 v150, 0xbfb8aa3b, v150
	v_mul_f32_e32 v151, 0xbfb8aa3b, v151
	v_exp_f32_e32 v148, v148
	v_exp_f32_e32 v149, v149
	v_exp_f32_e32 v150, v150
	v_exp_f32_e32 v151, v151
	v_add_f32_e32 v148, 1.0, v148
	v_add_f32_e32 v149, 1.0, v149
	v_add_f32_e32 v150, 1.0, v150
	v_add_f32_e32 v151, 1.0, v151
	v_rcp_f32_e32 v148, v148
	v_rcp_f32_e32 v149, v149
	v_rcp_f32_e32 v150, v150
	v_rcp_f32_e32 v151, v151
	s_nop 0
	v_cvt_pk_bf16_f32 v170, v148, v149
	v_cvt_pk_bf16_f32 v171, v150, v151
	s_nop 1
	v_permlane16_swap_b32 v168, v170
	v_permlane16_swap_b32 v169, v171
	s_nop 1
	global_store_dwordx4 v157, v[168:171], s[96:97] offset:64
	v_pk_add_f32 v[148:149], v[110:111], v[188:189]
	v_pk_add_f32 v[150:151], v[112:113], v[190:191]
	v_mul_f32_e32 v148, 0xbfb8aa3b, v148
	v_mul_f32_e32 v149, 0xbfb8aa3b, v149
	v_mul_f32_e32 v150, 0xbfb8aa3b, v150
	v_mul_f32_e32 v151, 0xbfb8aa3b, v151
	v_exp_f32_e32 v148, v148
	v_exp_f32_e32 v149, v149
	v_exp_f32_e32 v150, v150
	v_exp_f32_e32 v151, v151
	v_add_f32_e32 v148, 1.0, v148
	v_add_f32_e32 v149, 1.0, v149
	v_add_f32_e32 v150, 1.0, v150
	v_add_f32_e32 v151, 1.0, v151
	v_rcp_f32_e32 v148, v148
	v_rcp_f32_e32 v149, v149
	v_rcp_f32_e32 v150, v150
	v_rcp_f32_e32 v151, v151
	s_nop 0
	v_cvt_pk_bf16_f32 v164, v148, v149
	v_cvt_pk_bf16_f32 v165, v150, v151
	v_pk_add_f32 v[148:149], v[114:115], v[192:193]
	v_pk_add_f32 v[150:151], v[116:117], v[194:195]
	v_mul_f32_e32 v148, 0xbfb8aa3b, v148
	v_mul_f32_e32 v149, 0xbfb8aa3b, v149
	v_mul_f32_e32 v150, 0xbfb8aa3b, v150
	v_mul_f32_e32 v151, 0xbfb8aa3b, v151
	v_exp_f32_e32 v148, v148
	v_exp_f32_e32 v149, v149
	v_exp_f32_e32 v150, v150
	v_exp_f32_e32 v151, v151
	v_add_f32_e32 v148, 1.0, v148
	v_add_f32_e32 v149, 1.0, v149
	v_add_f32_e32 v150, 1.0, v150
	v_add_f32_e32 v151, 1.0, v151
	v_rcp_f32_e32 v148, v148
	v_rcp_f32_e32 v149, v149
	v_rcp_f32_e32 v150, v150
	v_rcp_f32_e32 v151, v151
	s_nop 0
	v_cvt_pk_bf16_f32 v166, v148, v149
	v_cvt_pk_bf16_f32 v167, v150, v151
	s_nop 1
	v_permlane16_swap_b32 v164, v166
	v_permlane16_swap_b32 v165, v167
	s_nop 1
	global_store_dwordx4 v158, v[164:167], s[96:97]
	v_pk_add_f32 v[148:149], v[118:119], v[208:209]
	v_pk_add_f32 v[150:151], v[120:121], v[210:211]
	v_mul_f32_e32 v148, 0xbfb8aa3b, v148
	v_mul_f32_e32 v149, 0xbfb8aa3b, v149
	v_mul_f32_e32 v150, 0xbfb8aa3b, v150
	v_mul_f32_e32 v151, 0xbfb8aa3b, v151
	v_exp_f32_e32 v148, v148
	v_exp_f32_e32 v149, v149
	v_exp_f32_e32 v150, v150
	v_exp_f32_e32 v151, v151
	v_add_f32_e32 v148, 1.0, v148
	v_add_f32_e32 v149, 1.0, v149
	v_add_f32_e32 v150, 1.0, v150
	v_add_f32_e32 v151, 1.0, v151
	v_rcp_f32_e32 v148, v148
	v_rcp_f32_e32 v149, v149
	v_rcp_f32_e32 v150, v150
	v_rcp_f32_e32 v151, v151
	s_nop 0
	v_cvt_pk_bf16_f32 v168, v148, v149
	v_cvt_pk_bf16_f32 v169, v150, v151
	v_pk_add_f32 v[148:149], v[122:123], v[212:213]
	v_pk_add_f32 v[150:151], v[124:125], v[214:215]
	v_mul_f32_e32 v148, 0xbfb8aa3b, v148
	v_mul_f32_e32 v149, 0xbfb8aa3b, v149
	v_mul_f32_e32 v150, 0xbfb8aa3b, v150
	v_mul_f32_e32 v151, 0xbfb8aa3b, v151
	v_exp_f32_e32 v148, v148
	v_exp_f32_e32 v149, v149
	v_exp_f32_e32 v150, v150
	v_exp_f32_e32 v151, v151
	v_add_f32_e32 v148, 1.0, v148
	v_add_f32_e32 v149, 1.0, v149
	v_add_f32_e32 v150, 1.0, v150
	v_add_f32_e32 v151, 1.0, v151
	v_rcp_f32_e32 v148, v148
	v_rcp_f32_e32 v149, v149
	v_rcp_f32_e32 v150, v150
	v_rcp_f32_e32 v151, v151
	s_nop 0
	v_cvt_pk_bf16_f32 v170, v148, v149
	v_cvt_pk_bf16_f32 v171, v150, v151
	s_nop 1
	v_permlane16_swap_b32 v168, v170
	v_permlane16_swap_b32 v169, v171
	s_nop 1
	global_store_dwordx4 v158, v[168:171], s[96:97] offset:64
	v_pk_add_f32 v[148:149], v[126:127], v[188:189]
	v_pk_add_f32 v[150:151], v[128:129], v[190:191]
	v_mul_f32_e32 v148, 0xbfb8aa3b, v148
	v_mul_f32_e32 v149, 0xbfb8aa3b, v149
	v_mul_f32_e32 v150, 0xbfb8aa3b, v150
	v_mul_f32_e32 v151, 0xbfb8aa3b, v151
	v_exp_f32_e32 v148, v148
	v_exp_f32_e32 v149, v149
	v_exp_f32_e32 v150, v150
	v_exp_f32_e32 v151, v151
	v_add_f32_e32 v148, 1.0, v148
	v_add_f32_e32 v149, 1.0, v149
	v_add_f32_e32 v150, 1.0, v150
	v_add_f32_e32 v151, 1.0, v151
	v_rcp_f32_e32 v148, v148
	v_rcp_f32_e32 v149, v149
	v_rcp_f32_e32 v150, v150
	v_rcp_f32_e32 v151, v151
	s_nop 0
	v_cvt_pk_bf16_f32 v164, v148, v149
	v_cvt_pk_bf16_f32 v165, v150, v151
	v_pk_add_f32 v[148:149], v[136:137], v[192:193]
	v_pk_add_f32 v[150:151], v[138:139], v[194:195]
	v_mul_f32_e32 v148, 0xbfb8aa3b, v148
	v_mul_f32_e32 v149, 0xbfb8aa3b, v149
	v_mul_f32_e32 v150, 0xbfb8aa3b, v150
	v_mul_f32_e32 v151, 0xbfb8aa3b, v151
	v_exp_f32_e32 v148, v148
	v_exp_f32_e32 v149, v149
	v_exp_f32_e32 v150, v150
	v_exp_f32_e32 v151, v151
	v_add_f32_e32 v148, 1.0, v148
	v_add_f32_e32 v149, 1.0, v149
	v_add_f32_e32 v150, 1.0, v150
	v_add_f32_e32 v151, 1.0, v151
	v_rcp_f32_e32 v148, v148
	v_rcp_f32_e32 v149, v149
	v_rcp_f32_e32 v150, v150
	v_rcp_f32_e32 v151, v151
	s_nop 0
	v_cvt_pk_bf16_f32 v166, v148, v149
	v_cvt_pk_bf16_f32 v167, v150, v151
	s_nop 1
	v_permlane16_swap_b32 v164, v166
	v_permlane16_swap_b32 v165, v167
	s_nop 1
	global_store_dwordx4 v159, v[164:167], s[96:97]
	v_pk_add_f32 v[148:149], v[140:141], v[208:209]
	v_pk_add_f32 v[150:151], v[142:143], v[210:211]
	v_mul_f32_e32 v148, 0xbfb8aa3b, v148
	v_mul_f32_e32 v149, 0xbfb8aa3b, v149
	v_mul_f32_e32 v150, 0xbfb8aa3b, v150
	v_mul_f32_e32 v151, 0xbfb8aa3b, v151
	v_exp_f32_e32 v148, v148
	v_exp_f32_e32 v149, v149
	v_exp_f32_e32 v150, v150
	v_exp_f32_e32 v151, v151
	v_add_f32_e32 v148, 1.0, v148
	v_add_f32_e32 v149, 1.0, v149
	v_add_f32_e32 v150, 1.0, v150
	v_add_f32_e32 v151, 1.0, v151
	v_rcp_f32_e32 v148, v148
	v_rcp_f32_e32 v149, v149
	v_rcp_f32_e32 v150, v150
	v_rcp_f32_e32 v151, v151
	s_nop 0
	v_cvt_pk_bf16_f32 v168, v148, v149
	v_cvt_pk_bf16_f32 v169, v150, v151
	v_pk_add_f32 v[148:149], v[144:145], v[212:213]
	v_pk_add_f32 v[150:151], v[146:147], v[214:215]
	v_mul_f32_e32 v148, 0xbfb8aa3b, v148
	v_mul_f32_e32 v149, 0xbfb8aa3b, v149
	v_mul_f32_e32 v150, 0xbfb8aa3b, v150
	v_mul_f32_e32 v151, 0xbfb8aa3b, v151
	v_exp_f32_e32 v148, v148
	v_exp_f32_e32 v149, v149
	v_exp_f32_e32 v150, v150
	v_exp_f32_e32 v151, v151
	v_add_f32_e32 v148, 1.0, v148
	v_add_f32_e32 v149, 1.0, v149
	v_add_f32_e32 v150, 1.0, v150
	v_add_f32_e32 v151, 1.0, v151
	v_rcp_f32_e32 v148, v148
	v_rcp_f32_e32 v149, v149
	v_rcp_f32_e32 v150, v150
	v_rcp_f32_e32 v151, v151
	s_nop 0
	v_cvt_pk_bf16_f32 v170, v148, v149
	v_cvt_pk_bf16_f32 v171, v150, v151
	s_nop 1
	v_permlane16_swap_b32 v168, v170
	v_permlane16_swap_b32 v169, v171
	s_nop 1
	global_store_dwordx4 v159, v[168:171], s[96:97] offset:64
	s_branch .Lg2_next
